# out-proj epilogue rewritten wide: acc through a wave-private LDS slab, dwordx4 x_in/x_out (65 instead of 258 VMEM instructions per wave and tile), loads one slab ahead
# speedup vs baseline: 1.0054x; 1.0022x over previous
.LBB0_57:
	s_cmp_gt_i32 s68, 0
	s_waitcnt vmcnt(6)
	s_cselect_b32 s69, -1, 2
	s_mul_i32 s70, s68, 0x6000
	s_waitcnt lgkmcnt(0)
	s_add_i32 s69, s69, s68
	v_add_u32_e32 v135, s70, v149
	v_add_u32_e32 v0, s70, v148
	s_mulk_i32 s69, 0x6000
	v_add_u32_e32 v164, v135, v152
	s_barrier
	v_lshl_add_u64 v[180:181], v[138:139], 0, s[0:1]
	v_add_u32_e32 v159, s69, v146
	v_lshl_add_u64 v[184:185], v[136:137], 0, s[0:1]
	v_add_u32_e32 v192, s69, v147
	v_add_u32_e32 v176, v0, v152
	ds_read_b128 v[140:143], v176
	ds_read_b128 v[160:163], v164
	ds_read_b128 v[164:167], v164 offset:2048
	v_lshl_add_u64 v[182:183], v[180:181], 0, s[88:89]
	v_lshl_add_u64 v[186:187], v[184:185], 0, s[88:89]
	v_add_u32_e32 v193, 0x4000, v192
	v_lshl_add_u64 v[188:189], v[180:181], 0, s[90:91]
	v_add_u32_e32 v194, 0x400, v159
	v_lshl_add_u64 v[190:191], v[180:181], 0, s[78:79]
	v_add_u32_e32 v195, 0x800, v159
	ds_read_b128 v[168:171], v176 offset:2048
	ds_read_b128 v[172:175], v176 offset:4096
	ds_read_b128 v[176:179], v176 offset:6144
	s_waitcnt lgkmcnt(3)
	s_setprio 1
	v_mfma_f32_32x32x16_bf16 v[114:129], v[140:143], v[160:163], v[114:129]
	v_mfma_f32_32x32x16_bf16 v[98:113], v[140:143], v[164:167], v[98:113]
	v_readfirstlane_b32 s69, v159
	s_mov_b32 m0, s69
	s_nop 0
	global_load_lds_dwordx4 v[182:183], off
	s_waitcnt lgkmcnt(2)
	v_mfma_f32_32x32x16_bf16 v[82:97], v[168:171], v[160:163], v[82:97]
	v_mfma_f32_32x32x16_bf16 v[66:81], v[168:171], v[164:167], v[66:81]
	v_readfirstlane_b32 s69, v194
	s_mov_b32 m0, s69
	s_nop 0
	global_load_lds_dwordx4 v[188:189], off
	s_waitcnt lgkmcnt(1)
	v_mfma_f32_32x32x16_bf16 v[50:65], v[172:175], v[160:163], v[50:65]
	v_mfma_f32_32x32x16_bf16 v[34:49], v[172:175], v[164:167], v[34:49]
	v_readfirstlane_b32 s69, v195
	s_mov_b32 m0, s69
	s_nop 0
	global_load_lds_dwordx4 v[190:191], off
	s_waitcnt lgkmcnt(0)
	v_mfma_f32_32x32x16_bf16 v[18:33], v[176:179], v[160:163], v[18:33]
	v_mfma_f32_32x32x16_bf16 v[2:17], v[176:179], v[164:167], v[2:17]
	s_setprio 0
	v_add_u32_e32 v0, v0, v153
	v_add_u32_e32 v135, v135, v153
	ds_read_b128 v[140:143], v0
	ds_read_b128 v[160:163], v135
	ds_read_b128 v[164:167], v135 offset:2048
	ds_read_b128 v[168:171], v0 offset:2048
	ds_read_b128 v[172:175], v0 offset:4096
	ds_read_b128 v[176:179], v0 offset:6144
	s_waitcnt lgkmcnt(3)
	s_setprio 1
	v_mfma_f32_32x32x16_bf16 v[114:129], v[140:143], v[160:163], v[114:129]
	v_mfma_f32_32x32x16_bf16 v[98:113], v[140:143], v[164:167], v[98:113]
	v_add_u32_e32 v0, 0xc00, v159
	v_lshl_add_u64 v[140:141], v[180:181], 0, s[76:77]
	v_readfirstlane_b32 s69, v0
	s_mov_b32 m0, s69
	s_nop 0
	global_load_lds_dwordx4 v[140:141], off
	s_waitcnt lgkmcnt(2)
	v_mfma_f32_32x32x16_bf16 v[82:97], v[168:171], v[160:163], v[82:97]
	v_mfma_f32_32x32x16_bf16 v[66:81], v[168:171], v[164:167], v[66:81]
	v_readfirstlane_b32 s69, v193
	s_mov_b32 m0, s69
	s_nop 0
	global_load_lds_dwordx4 v[186:187], off
	s_waitcnt lgkmcnt(1)
	v_mfma_f32_32x32x16_bf16 v[50:65], v[172:175], v[160:163], v[50:65]
	v_mfma_f32_32x32x16_bf16 v[34:49], v[172:175], v[164:167], v[34:49]
	v_add_u32_e32 v0, 0x4400, v192
	v_lshl_add_u64 v[140:141], v[184:185], 0, s[90:91]
	v_readfirstlane_b32 s69, v0
	s_mov_b32 m0, s69
	s_nop 0
	global_load_lds_dwordx4 v[140:141], off
	s_waitcnt lgkmcnt(0)
	v_mfma_f32_32x32x16_bf16 v[18:33], v[176:179], v[160:163], v[18:33]
	v_mfma_f32_32x32x16_bf16 v[2:17], v[176:179], v[164:167], v[2:17]
	s_setprio 0
	s_add_i32 s69, s68, 1
	s_cmp_lt_i32 s68, 2
	s_cselect_b32 s68, s69, 0
	s_add_u32 s0, s0, 0x80
	s_addc_u32 s1, s1, 0
	s_cmpk_eq_i32 s0, 0xf00
	s_cbranch_scc0 .LBB0_57
	s_waitcnt vmcnt(6)
	s_mul_i32 s0, s68, 0x6000
	s_waitcnt lgkmcnt(0)
	v_add_u32_e32 v135, s0, v149
	v_add_u32_e32 v0, s0, v148
	v_add_u32_e32 v160, v135, v152
	s_barrier
	v_add_u32_e32 v159, v0, v152
	ds_read_b128 v[136:139], v159
	ds_read_b128 v[140:143], v160
	ds_read_b128 v[160:163], v160 offset:2048
	ds_read_b128 v[164:167], v159 offset:2048
	ds_read_b128 v[168:171], v159 offset:4096
	ds_read_b128 v[172:175], v159 offset:6144
	s_waitcnt lgkmcnt(3)
	s_setprio 1
	v_mfma_f32_32x32x16_bf16 v[114:129], v[136:139], v[140:143], v[114:129]
	v_mfma_f32_32x32x16_bf16 v[98:113], v[136:139], v[160:163], v[98:113]
	s_waitcnt lgkmcnt(2)
	v_mfma_f32_32x32x16_bf16 v[82:97], v[164:167], v[140:143], v[82:97]
	v_mfma_f32_32x32x16_bf16 v[66:81], v[164:167], v[160:163], v[66:81]
	s_waitcnt lgkmcnt(1)
	v_mfma_f32_32x32x16_bf16 v[50:65], v[168:171], v[140:143], v[50:65]
	v_mfma_f32_32x32x16_bf16 v[34:49], v[168:171], v[160:163], v[34:49]
	s_waitcnt lgkmcnt(0)
	v_mfma_f32_32x32x16_bf16 v[18:33], v[172:175], v[140:143], v[18:33]
	v_mfma_f32_32x32x16_bf16 v[2:17], v[172:175], v[160:163], v[2:17]
	s_setprio 0
	v_add_u32_e32 v0, v0, v153
	v_add_u32_e32 v135, v135, v153
	ds_read_b128 v[136:139], v0
	ds_read_b128 v[140:143], v135
	ds_read_b128 v[160:163], v135 offset:2048
	ds_read_b128 v[164:167], v0 offset:2048
	ds_read_b128 v[168:171], v0 offset:4096
	ds_read_b128 v[172:175], v0 offset:6144
	s_waitcnt lgkmcnt(3)
	s_setprio 1
	v_mfma_f32_32x32x16_bf16 v[114:129], v[136:139], v[140:143], v[114:129]
	v_mfma_f32_32x32x16_bf16 v[98:113], v[136:139], v[160:163], v[98:113]
	s_waitcnt lgkmcnt(2)
	v_mfma_f32_32x32x16_bf16 v[82:97], v[164:167], v[140:143], v[82:97]
	v_mfma_f32_32x32x16_bf16 v[66:81], v[164:167], v[160:163], v[66:81]
	s_waitcnt lgkmcnt(1)
	v_mfma_f32_32x32x16_bf16 v[50:65], v[168:171], v[140:143], v[50:65]
	v_mfma_f32_32x32x16_bf16 v[34:49], v[168:171], v[160:163], v[34:49]
	s_waitcnt lgkmcnt(0)
	v_mfma_f32_32x32x16_bf16 v[18:33], v[172:175], v[140:143], v[18:33]
	v_mfma_f32_32x32x16_bf16 v[2:17], v[172:175], v[160:163], v[2:17]
	s_setprio 0
	s_waitcnt vmcnt(0)
	s_waitcnt lgkmcnt(0)
	s_barrier
	ds_read_b128 v[136:139], v154
	ds_read_b128 v[140:143], v155
	ds_read_b128 v[160:163], v155 offset:2048
	ds_read_b128 v[164:167], v154 offset:2048
	ds_read_b128 v[168:171], v154 offset:4096
	ds_read_b128 v[172:175], v154 offset:6144
	s_waitcnt lgkmcnt(3)
	s_setprio 1
	v_mfma_f32_32x32x16_bf16 v[114:129], v[136:139], v[140:143], v[114:129]
	v_mfma_f32_32x32x16_bf16 v[98:113], v[136:139], v[160:163], v[98:113]
	s_waitcnt lgkmcnt(2)
	v_mfma_f32_32x32x16_bf16 v[82:97], v[164:167], v[140:143], v[82:97]
	v_mfma_f32_32x32x16_bf16 v[66:81], v[164:167], v[160:163], v[66:81]
	s_waitcnt lgkmcnt(1)
	v_mfma_f32_32x32x16_bf16 v[50:65], v[168:171], v[140:143], v[50:65]
	v_mfma_f32_32x32x16_bf16 v[34:49], v[168:171], v[160:163], v[34:49]
	s_waitcnt lgkmcnt(0)
	v_mfma_f32_32x32x16_bf16 v[18:33], v[172:175], v[140:143], v[18:33]
	v_mfma_f32_32x32x16_bf16 v[2:17], v[172:175], v[160:163], v[2:17]
	s_setprio 0
	ds_read_b128 v[136:139], v156
	ds_read_b128 v[140:143], v157
	ds_read_b128 v[160:163], v157 offset:2048
	ds_read_b128 v[164:167], v156 offset:2048
	ds_read_b128 v[168:171], v156 offset:4096
	ds_read_b128 v[172:175], v156 offset:6144
	s_waitcnt lgkmcnt(3)
	s_setprio 1
	v_mfma_f32_32x32x16_bf16 v[114:129], v[136:139], v[140:143], v[114:129]
	v_mfma_f32_32x32x16_bf16 v[98:113], v[136:139], v[160:163], v[98:113]
	s_waitcnt lgkmcnt(2)
	v_mfma_f32_32x32x16_bf16 v[82:97], v[164:167], v[140:143], v[82:97]
	v_mfma_f32_32x32x16_bf16 v[66:81], v[164:167], v[160:163], v[66:81]
	s_waitcnt lgkmcnt(1)
	v_mfma_f32_32x32x16_bf16 v[50:65], v[168:171], v[140:143], v[50:65]
	v_mfma_f32_32x32x16_bf16 v[34:49], v[168:171], v[160:163], v[34:49]
	s_waitcnt lgkmcnt(0)
	v_mfma_f32_32x32x16_bf16 v[18:33], v[172:175], v[140:143], v[18:33]
	v_mfma_f32_32x32x16_bf16 v[2:17], v[172:175], v[160:163], v[2:17]
	s_setprio 0
	v_add_u32_e32 v138, s29, v151
	v_or_b32_e32 v136, s31, v150
	v_ashrrev_i32_e32 v139, 31, v138
	v_lshlrev_b64 v[142:143], 10, v[138:139]
	v_ashrrev_i32_e32 v137, 31, v136
	v_lshl_add_u64 v[142:143], v[142:143], 0, v[136:137]
	s_ashr_i32 s0, s28, 4
	v_lshlrev_b64 v[160:161], 2, v[142:143]
	s_add_i32 s0, s0, s10
	v_lshl_add_u64 v[142:143], s[98:99], 0, v[160:161]
	s_movk_i32 s29, 0x2000
	s_mul_hi_i32 s1, s0, 0x3000
	s_mulk_i32 s0, 0x3000
	v_add_co_u32_e32 v162, vcc, s29, v142
	s_add_u32 s0, s4, s0
	s_nop 0
	v_addc_co_u32_e32 v163, vcc, 0, v143, vcc
	s_addc_u32 s1, s5, s1
	v_add_co_u32_e32 v164, vcc, s73, v142
	s_add_u32 s0, s0, 0x2000
	s_nop 0
	v_addc_co_u32_e32 v165, vcc, 0, v143, vcc
	s_addc_u32 s1, s1, 0
	v_add_co_u32_e32 v166, vcc, s75, v142
	v_lshl_add_u64 v[140:141], v[136:137], 2, s[0:1]
	s_nop 0
	v_addc_co_u32_e32 v167, vcc, 0, v143, vcc
	s_waitcnt vmcnt(0) lgkmcnt(0)
	s_barrier
	v_and_b32_e32 v198, 63, v200
	v_lshrrev_b32_e32 v199, 5, v198
	v_and_b32_e32 v130, 31, v198
	v_lshlrev_b32_e32 v131, 2, v199
	v_sub_u32_e32 v138, v138, v131
	v_sub_u32_e32 v136, v136, v130
	v_lshrrev_b32_e32 v131, 6, v200
	v_mul_u32_u24_e32 v131, 0x2200, v131
	v_lshlrev_b32_e32 v130, 2, v130
	s_movk_i32 s28, 0x440
	v_mad_u32_u24 v130, v199, s28, v130
	v_add_u32_e32 v130, v130, v131
	v_lshrrev_b32_e32 v199, 4, v198
	v_and_b32_e32 v198, 15, v198
	s_movk_i32 s28, 0x110
	v_mad_u32_u24 v131, v199, s28, v131
	v_lshl_add_u32 v131, v198, 4, v131
	v_add_u32_e32 v138, v138, v199
	v_lshl_add_u32 v136, v198, 2, v136
	v_lshlrev_b32_e32 v198, 2, v136
	global_load_dwordx4 v[196:199], v198, s[0:1]
	v_lshl_add_u32 v0, v138, 10, v136
	v_lshlrev_b32_e32 v0, 2, v0
	s_mov_b64 s[36:37], s[98:99]
	s_mov_b64 s[38:39], s[56:57]
	global_load_dwordx4 v[132:135], v0, s[36:37] nt
	s_add_u32 s36, s36, 0x4000
	s_addc_u32 s37, s37, 0
	global_load_dwordx4 v[136:139], v0, s[36:37] nt
	s_add_u32 s36, s36, 0x4000
	s_addc_u32 s37, s37, 0
	global_load_dwordx4 v[140:143], v0, s[36:37] nt
	s_add_u32 s36, s36, 0x4000
	s_addc_u32 s37, s37, 0
	global_load_dwordx4 v[144:147], v0, s[36:37] nt
	s_add_u32 s36, s36, 0x4000
	s_addc_u32 s37, s37, 0
	global_load_dwordx4 v[148:151], v0, s[36:37] nt
	s_add_u32 s36, s36, 0x4000
	s_addc_u32 s37, s37, 0
	global_load_dwordx4 v[152:155], v0, s[36:37] nt
	s_add_u32 s36, s36, 0x4000
	s_addc_u32 s37, s37, 0
	global_load_dwordx4 v[156:159], v0, s[36:37] nt
	s_add_u32 s36, s36, 0x4000
	s_addc_u32 s37, s37, 0
	global_load_dwordx4 v[160:163], v0, s[36:37] nt
	s_add_u32 s36, s36, 0x4000
	s_addc_u32 s37, s37, 0
	global_load_dwordx4 v[164:167], v0, s[36:37] nt
	s_add_u32 s36, s36, 0x4000
	s_addc_u32 s37, s37, 0
	global_load_dwordx4 v[168:171], v0, s[36:37] nt
	s_add_u32 s36, s36, 0x4000
	s_addc_u32 s37, s37, 0
	global_load_dwordx4 v[172:175], v0, s[36:37] nt
	s_add_u32 s36, s36, 0x4000
	s_addc_u32 s37, s37, 0
	global_load_dwordx4 v[176:179], v0, s[36:37] nt
	s_add_u32 s36, s36, 0x4000
	s_addc_u32 s37, s37, 0
	global_load_dwordx4 v[180:183], v0, s[36:37] nt
	s_add_u32 s36, s36, 0x4000
	s_addc_u32 s37, s37, 0
	global_load_dwordx4 v[184:187], v0, s[36:37] nt
	s_add_u32 s36, s36, 0x4000
	s_addc_u32 s37, s37, 0
	global_load_dwordx4 v[188:191], v0, s[36:37] nt
	s_add_u32 s36, s36, 0x4000
	s_addc_u32 s37, s37, 0
	global_load_dwordx4 v[192:195], v0, s[36:37] nt
	s_add_u32 s36, s36, 0x4000
	s_addc_u32 s37, s37, 0
	ds_write2_b32 v130, v114, v98 offset0:0 offset1:32
	ds_write2_b32 v130, v115, v99 offset0:68 offset1:100
	ds_write2_b32 v130, v116, v100 offset0:136 offset1:168
	ds_write2_b32 v130, v117, v101 offset0:204 offset1:236
	v_add_u32_e32 v130, 0x880, v130
	ds_write2_b32 v130, v118, v102 offset0:0 offset1:32
	ds_write2_b32 v130, v119, v103 offset0:68 offset1:100
	ds_write2_b32 v130, v120, v104 offset0:136 offset1:168
	ds_write2_b32 v130, v121, v105 offset0:204 offset1:236
	v_add_u32_e32 v130, 0x880, v130
	ds_write2_b32 v130, v122, v106 offset0:0 offset1:32
	ds_write2_b32 v130, v123, v107 offset0:68 offset1:100
	ds_write2_b32 v130, v124, v108 offset0:136 offset1:168
	ds_write2_b32 v130, v125, v109 offset0:204 offset1:236
	v_add_u32_e32 v130, 0x880, v130
	ds_write2_b32 v130, v126, v110 offset0:0 offset1:32
	ds_write2_b32 v130, v127, v111 offset0:68 offset1:100
	ds_write2_b32 v130, v128, v112 offset0:136 offset1:168
	ds_write2_b32 v130, v129, v113 offset0:204 offset1:236
	v_subrev_u32_e32 v130, 0x1980, v130
	s_waitcnt lgkmcnt(0)
	ds_read_b128 v[98:101], v131
	ds_read_b128 v[102:105], v131 offset:1088
	ds_read_b128 v[106:109], v131 offset:2176
	ds_read_b128 v[110:113], v131 offset:3264
	ds_read_b128 v[114:117], v131 offset:4352
	ds_read_b128 v[118:121], v131 offset:5440
	ds_read_b128 v[122:125], v131 offset:6528
	ds_read_b128 v[126:129], v131 offset:7616
	s_waitcnt vmcnt(8) lgkmcnt(0)
	v_fmac_f32_e32 v132, v98, v196
	v_fmac_f32_e32 v133, v99, v197
	v_fmac_f32_e32 v134, v100, v198
	v_fmac_f32_e32 v135, v101, v199
	global_store_dwordx4 v0, v[132:135], s[38:39] nt
	s_add_u32 s38, s38, 0x4000
	s_addc_u32 s39, s39, 0
	v_fmac_f32_e32 v136, v102, v196
	v_fmac_f32_e32 v137, v103, v197
	v_fmac_f32_e32 v138, v104, v198
	v_fmac_f32_e32 v139, v105, v199
	global_store_dwordx4 v0, v[136:139], s[38:39] nt
	s_add_u32 s38, s38, 0x4000
	s_addc_u32 s39, s39, 0
	v_fmac_f32_e32 v140, v106, v196
	v_fmac_f32_e32 v141, v107, v197
	v_fmac_f32_e32 v142, v108, v198
	v_fmac_f32_e32 v143, v109, v199
	global_store_dwordx4 v0, v[140:143], s[38:39] nt
	s_add_u32 s38, s38, 0x4000
	s_addc_u32 s39, s39, 0
	v_fmac_f32_e32 v144, v110, v196
	v_fmac_f32_e32 v145, v111, v197
	v_fmac_f32_e32 v146, v112, v198
	v_fmac_f32_e32 v147, v113, v199
	global_store_dwordx4 v0, v[144:147], s[38:39] nt
	s_add_u32 s38, s38, 0x4000
	s_addc_u32 s39, s39, 0
	v_fmac_f32_e32 v148, v114, v196
	v_fmac_f32_e32 v149, v115, v197
	v_fmac_f32_e32 v150, v116, v198
	v_fmac_f32_e32 v151, v117, v199
	global_store_dwordx4 v0, v[148:151], s[38:39] nt
	s_add_u32 s38, s38, 0x4000
	s_addc_u32 s39, s39, 0
	v_fmac_f32_e32 v152, v118, v196
	v_fmac_f32_e32 v153, v119, v197
	v_fmac_f32_e32 v154, v120, v198
	v_fmac_f32_e32 v155, v121, v199
	global_store_dwordx4 v0, v[152:155], s[38:39] nt
	s_add_u32 s38, s38, 0x4000
	s_addc_u32 s39, s39, 0
	v_fmac_f32_e32 v156, v122, v196
	v_fmac_f32_e32 v157, v123, v197
	v_fmac_f32_e32 v158, v124, v198
	v_fmac_f32_e32 v159, v125, v199
	global_store_dwordx4 v0, v[156:159], s[38:39] nt
	s_add_u32 s38, s38, 0x4000
	s_addc_u32 s39, s39, 0
	v_fmac_f32_e32 v160, v126, v196
	v_fmac_f32_e32 v161, v127, v197
	v_fmac_f32_e32 v162, v128, v198
	v_fmac_f32_e32 v163, v129, v199
	global_store_dwordx4 v0, v[160:163], s[38:39] nt
	s_add_u32 s38, s38, 0x4000
	s_addc_u32 s39, s39, 0
	global_load_dwordx4 v[132:135], v0, s[36:37] nt
	s_add_u32 s36, s36, 0x4000
	s_addc_u32 s37, s37, 0
	global_load_dwordx4 v[136:139], v0, s[36:37] nt
	s_add_u32 s36, s36, 0x4000
	s_addc_u32 s37, s37, 0
	global_load_dwordx4 v[140:143], v0, s[36:37] nt
	s_add_u32 s36, s36, 0x4000
	s_addc_u32 s37, s37, 0
	global_load_dwordx4 v[144:147], v0, s[36:37] nt
	s_add_u32 s36, s36, 0x4000
	s_addc_u32 s37, s37, 0
	global_load_dwordx4 v[148:151], v0, s[36:37] nt
	s_add_u32 s36, s36, 0x4000
	s_addc_u32 s37, s37, 0
	global_load_dwordx4 v[152:155], v0, s[36:37] nt
	s_add_u32 s36, s36, 0x4000
	s_addc_u32 s37, s37, 0
	global_load_dwordx4 v[156:159], v0, s[36:37] nt
	s_add_u32 s36, s36, 0x4000
	s_addc_u32 s37, s37, 0
	global_load_dwordx4 v[160:163], v0, s[36:37] nt
	s_add_u32 s36, s36, 0x4000
	s_addc_u32 s37, s37, 0
	ds_write2_b32 v130, v82, v66 offset0:0 offset1:32
	ds_write2_b32 v130, v83, v67 offset0:68 offset1:100
	ds_write2_b32 v130, v84, v68 offset0:136 offset1:168
	ds_write2_b32 v130, v85, v69 offset0:204 offset1:236
	v_add_u32_e32 v130, 0x880, v130
	ds_write2_b32 v130, v86, v70 offset0:0 offset1:32
	ds_write2_b32 v130, v87, v71 offset0:68 offset1:100
	ds_write2_b32 v130, v88, v72 offset0:136 offset1:168
	ds_write2_b32 v130, v89, v73 offset0:204 offset1:236
	v_add_u32_e32 v130, 0x880, v130
	ds_write2_b32 v130, v90, v74 offset0:0 offset1:32
	ds_write2_b32 v130, v91, v75 offset0:68 offset1:100
	ds_write2_b32 v130, v92, v76 offset0:136 offset1:168
	ds_write2_b32 v130, v93, v77 offset0:204 offset1:236
	v_add_u32_e32 v130, 0x880, v130
	ds_write2_b32 v130, v94, v78 offset0:0 offset1:32
	ds_write2_b32 v130, v95, v79 offset0:68 offset1:100
	ds_write2_b32 v130, v96, v80 offset0:136 offset1:168
	ds_write2_b32 v130, v97, v81 offset0:204 offset1:236
	v_subrev_u32_e32 v130, 0x1980, v130
	s_waitcnt lgkmcnt(0)
	ds_read_b128 v[66:69], v131
	ds_read_b128 v[70:73], v131 offset:1088
	ds_read_b128 v[74:77], v131 offset:2176
	ds_read_b128 v[78:81], v131 offset:3264
	ds_read_b128 v[82:85], v131 offset:4352
	ds_read_b128 v[86:89], v131 offset:5440
	ds_read_b128 v[90:93], v131 offset:6528
	ds_read_b128 v[94:97], v131 offset:7616
	s_waitcnt vmcnt(16) lgkmcnt(0)
	v_fmac_f32_e32 v164, v66, v196
	v_fmac_f32_e32 v165, v67, v197
	v_fmac_f32_e32 v166, v68, v198
	v_fmac_f32_e32 v167, v69, v199
	global_store_dwordx4 v0, v[164:167], s[38:39] nt
	s_add_u32 s38, s38, 0x4000
	s_addc_u32 s39, s39, 0
	v_fmac_f32_e32 v168, v70, v196
	v_fmac_f32_e32 v169, v71, v197
	v_fmac_f32_e32 v170, v72, v198
	v_fmac_f32_e32 v171, v73, v199
	global_store_dwordx4 v0, v[168:171], s[38:39] nt
	s_add_u32 s38, s38, 0x4000
	s_addc_u32 s39, s39, 0
	v_fmac_f32_e32 v172, v74, v196
	v_fmac_f32_e32 v173, v75, v197
	v_fmac_f32_e32 v174, v76, v198
	v_fmac_f32_e32 v175, v77, v199
	global_store_dwordx4 v0, v[172:175], s[38:39] nt
	s_add_u32 s38, s38, 0x4000
	s_addc_u32 s39, s39, 0
	v_fmac_f32_e32 v176, v78, v196
	v_fmac_f32_e32 v177, v79, v197
	v_fmac_f32_e32 v178, v80, v198
	v_fmac_f32_e32 v179, v81, v199
	global_store_dwordx4 v0, v[176:179], s[38:39] nt
	s_add_u32 s38, s38, 0x4000
	s_addc_u32 s39, s39, 0
	v_fmac_f32_e32 v180, v82, v196
	v_fmac_f32_e32 v181, v83, v197
	v_fmac_f32_e32 v182, v84, v198
	v_fmac_f32_e32 v183, v85, v199
	global_store_dwordx4 v0, v[180:183], s[38:39] nt
	s_add_u32 s38, s38, 0x4000
	s_addc_u32 s39, s39, 0
	v_fmac_f32_e32 v184, v86, v196
	v_fmac_f32_e32 v185, v87, v197
	v_fmac_f32_e32 v186, v88, v198
	v_fmac_f32_e32 v187, v89, v199
	global_store_dwordx4 v0, v[184:187], s[38:39] nt
	s_add_u32 s38, s38, 0x4000
	s_addc_u32 s39, s39, 0
	v_fmac_f32_e32 v188, v90, v196
	v_fmac_f32_e32 v189, v91, v197
	v_fmac_f32_e32 v190, v92, v198
	v_fmac_f32_e32 v191, v93, v199
	global_store_dwordx4 v0, v[188:191], s[38:39] nt
	s_add_u32 s38, s38, 0x4000
	s_addc_u32 s39, s39, 0
	v_fmac_f32_e32 v192, v94, v196
	v_fmac_f32_e32 v193, v95, v197
	v_fmac_f32_e32 v194, v96, v198
	v_fmac_f32_e32 v195, v97, v199
	global_store_dwordx4 v0, v[192:195], s[38:39] nt
	s_add_u32 s38, s38, 0x4000
	s_addc_u32 s39, s39, 0
	global_load_dwordx4 v[164:167], v0, s[36:37] nt
	s_add_u32 s36, s36, 0x4000
	s_addc_u32 s37, s37, 0
	global_load_dwordx4 v[168:171], v0, s[36:37] nt
	s_add_u32 s36, s36, 0x4000
	s_addc_u32 s37, s37, 0
	global_load_dwordx4 v[172:175], v0, s[36:37] nt
	s_add_u32 s36, s36, 0x4000
	s_addc_u32 s37, s37, 0
	global_load_dwordx4 v[176:179], v0, s[36:37] nt
	s_add_u32 s36, s36, 0x4000
	s_addc_u32 s37, s37, 0
	global_load_dwordx4 v[180:183], v0, s[36:37] nt
	s_add_u32 s36, s36, 0x4000
	s_addc_u32 s37, s37, 0
	global_load_dwordx4 v[184:187], v0, s[36:37] nt
	s_add_u32 s36, s36, 0x4000
	s_addc_u32 s37, s37, 0
	global_load_dwordx4 v[188:191], v0, s[36:37] nt
	s_add_u32 s36, s36, 0x4000
	s_addc_u32 s37, s37, 0
	global_load_dwordx4 v[192:195], v0, s[36:37] nt
	s_add_u32 s36, s36, 0x4000
	s_addc_u32 s37, s37, 0
	ds_write2_b32 v130, v50, v34 offset0:0 offset1:32
	ds_write2_b32 v130, v51, v35 offset0:68 offset1:100
	ds_write2_b32 v130, v52, v36 offset0:136 offset1:168
	ds_write2_b32 v130, v53, v37 offset0:204 offset1:236
	v_add_u32_e32 v130, 0x880, v130
	ds_write2_b32 v130, v54, v38 offset0:0 offset1:32
	ds_write2_b32 v130, v55, v39 offset0:68 offset1:100
	ds_write2_b32 v130, v56, v40 offset0:136 offset1:168
	ds_write2_b32 v130, v57, v41 offset0:204 offset1:236
	v_add_u32_e32 v130, 0x880, v130
	ds_write2_b32 v130, v58, v42 offset0:0 offset1:32
	ds_write2_b32 v130, v59, v43 offset0:68 offset1:100
	ds_write2_b32 v130, v60, v44 offset0:136 offset1:168
	ds_write2_b32 v130, v61, v45 offset0:204 offset1:236
	v_add_u32_e32 v130, 0x880, v130
	ds_write2_b32 v130, v62, v46 offset0:0 offset1:32
	ds_write2_b32 v130, v63, v47 offset0:68 offset1:100
	ds_write2_b32 v130, v64, v48 offset0:136 offset1:168
	ds_write2_b32 v130, v65, v49 offset0:204 offset1:236
	v_subrev_u32_e32 v130, 0x1980, v130
	s_waitcnt lgkmcnt(0)
	ds_read_b128 v[34:37], v131
	ds_read_b128 v[38:41], v131 offset:1088
	ds_read_b128 v[42:45], v131 offset:2176
	ds_read_b128 v[46:49], v131 offset:3264
	ds_read_b128 v[50:53], v131 offset:4352
	ds_read_b128 v[54:57], v131 offset:5440
	ds_read_b128 v[58:61], v131 offset:6528
	ds_read_b128 v[62:65], v131 offset:7616
	s_waitcnt vmcnt(16) lgkmcnt(0)
	v_fmac_f32_e32 v132, v34, v196
	v_fmac_f32_e32 v133, v35, v197
	v_fmac_f32_e32 v134, v36, v198
	v_fmac_f32_e32 v135, v37, v199
	global_store_dwordx4 v0, v[132:135], s[38:39] nt
	s_add_u32 s38, s38, 0x4000
	s_addc_u32 s39, s39, 0
	v_fmac_f32_e32 v136, v38, v196
	v_fmac_f32_e32 v137, v39, v197
	v_fmac_f32_e32 v138, v40, v198
	v_fmac_f32_e32 v139, v41, v199
	global_store_dwordx4 v0, v[136:139], s[38:39] nt
	s_add_u32 s38, s38, 0x4000
	s_addc_u32 s39, s39, 0
	v_fmac_f32_e32 v140, v42, v196
	v_fmac_f32_e32 v141, v43, v197
	v_fmac_f32_e32 v142, v44, v198
	v_fmac_f32_e32 v143, v45, v199
	global_store_dwordx4 v0, v[140:143], s[38:39] nt
	s_add_u32 s38, s38, 0x4000
	s_addc_u32 s39, s39, 0
	v_fmac_f32_e32 v144, v46, v196
	v_fmac_f32_e32 v145, v47, v197
	v_fmac_f32_e32 v146, v48, v198
	v_fmac_f32_e32 v147, v49, v199
	global_store_dwordx4 v0, v[144:147], s[38:39] nt
	s_add_u32 s38, s38, 0x4000
	s_addc_u32 s39, s39, 0
	v_fmac_f32_e32 v148, v50, v196
	v_fmac_f32_e32 v149, v51, v197
	v_fmac_f32_e32 v150, v52, v198
	v_fmac_f32_e32 v151, v53, v199
	global_store_dwordx4 v0, v[148:151], s[38:39] nt
	s_add_u32 s38, s38, 0x4000
	s_addc_u32 s39, s39, 0
	v_fmac_f32_e32 v152, v54, v196
	v_fmac_f32_e32 v153, v55, v197
	v_fmac_f32_e32 v154, v56, v198
	v_fmac_f32_e32 v155, v57, v199
	global_store_dwordx4 v0, v[152:155], s[38:39] nt
	s_add_u32 s38, s38, 0x4000
	s_addc_u32 s39, s39, 0
	v_fmac_f32_e32 v156, v58, v196
	v_fmac_f32_e32 v157, v59, v197
	v_fmac_f32_e32 v158, v60, v198
	v_fmac_f32_e32 v159, v61, v199
	global_store_dwordx4 v0, v[156:159], s[38:39] nt
	s_add_u32 s38, s38, 0x4000
	s_addc_u32 s39, s39, 0
	v_fmac_f32_e32 v160, v62, v196
	v_fmac_f32_e32 v161, v63, v197
	v_fmac_f32_e32 v162, v64, v198
	v_fmac_f32_e32 v163, v65, v199
	global_store_dwordx4 v0, v[160:163], s[38:39] nt
	s_add_u32 s38, s38, 0x4000
	s_addc_u32 s39, s39, 0
	ds_write2_b32 v130, v18, v2 offset0:0 offset1:32
	ds_write2_b32 v130, v19, v3 offset0:68 offset1:100
	ds_write2_b32 v130, v20, v4 offset0:136 offset1:168
	ds_write2_b32 v130, v21, v5 offset0:204 offset1:236
	v_add_u32_e32 v130, 0x880, v130
	ds_write2_b32 v130, v22, v6 offset0:0 offset1:32
	ds_write2_b32 v130, v23, v7 offset0:68 offset1:100
	ds_write2_b32 v130, v24, v8 offset0:136 offset1:168
	ds_write2_b32 v130, v25, v9 offset0:204 offset1:236
	v_add_u32_e32 v130, 0x880, v130
	ds_write2_b32 v130, v26, v10 offset0:0 offset1:32
	ds_write2_b32 v130, v27, v11 offset0:68 offset1:100
	ds_write2_b32 v130, v28, v12 offset0:136 offset1:168
	ds_write2_b32 v130, v29, v13 offset0:204 offset1:236
	v_add_u32_e32 v130, 0x880, v130
	ds_write2_b32 v130, v30, v14 offset0:0 offset1:32
	ds_write2_b32 v130, v31, v15 offset0:68 offset1:100
	ds_write2_b32 v130, v32, v16 offset0:136 offset1:168
	ds_write2_b32 v130, v33, v17 offset0:204 offset1:236
	v_subrev_u32_e32 v130, 0x1980, v130
	s_waitcnt lgkmcnt(0)
	ds_read_b128 v[2:5], v131
	ds_read_b128 v[6:9], v131 offset:1088
	ds_read_b128 v[10:13], v131 offset:2176
	ds_read_b128 v[14:17], v131 offset:3264
	ds_read_b128 v[18:21], v131 offset:4352
	ds_read_b128 v[22:25], v131 offset:5440
	ds_read_b128 v[26:29], v131 offset:6528
	ds_read_b128 v[30:33], v131 offset:7616
	s_waitcnt vmcnt(8) lgkmcnt(0)
	v_fmac_f32_e32 v164, v2, v196
	v_fmac_f32_e32 v165, v3, v197
	v_fmac_f32_e32 v166, v4, v198
	v_fmac_f32_e32 v167, v5, v199
	global_store_dwordx4 v0, v[164:167], s[38:39] nt
	s_add_u32 s38, s38, 0x4000
	s_addc_u32 s39, s39, 0
	v_fmac_f32_e32 v168, v6, v196
	v_fmac_f32_e32 v169, v7, v197
	v_fmac_f32_e32 v170, v8, v198
	v_fmac_f32_e32 v171, v9, v199
	global_store_dwordx4 v0, v[168:171], s[38:39] nt
	s_add_u32 s38, s38, 0x4000
	s_addc_u32 s39, s39, 0
	v_fmac_f32_e32 v172, v10, v196
	v_fmac_f32_e32 v173, v11, v197
	v_fmac_f32_e32 v174, v12, v198
	v_fmac_f32_e32 v175, v13, v199
	global_store_dwordx4 v0, v[172:175], s[38:39] nt
	s_add_u32 s38, s38, 0x4000
	s_addc_u32 s39, s39, 0
	v_fmac_f32_e32 v176, v14, v196
	v_fmac_f32_e32 v177, v15, v197
	v_fmac_f32_e32 v178, v16, v198
	v_fmac_f32_e32 v179, v17, v199
	global_store_dwordx4 v0, v[176:179], s[38:39] nt
	s_add_u32 s38, s38, 0x4000
	s_addc_u32 s39, s39, 0
	v_fmac_f32_e32 v180, v18, v196
	v_fmac_f32_e32 v181, v19, v197
	v_fmac_f32_e32 v182, v20, v198
	v_fmac_f32_e32 v183, v21, v199
	global_store_dwordx4 v0, v[180:183], s[38:39] nt
	s_add_u32 s38, s38, 0x4000
	s_addc_u32 s39, s39, 0
	v_fmac_f32_e32 v184, v22, v196
	v_fmac_f32_e32 v185, v23, v197
	v_fmac_f32_e32 v186, v24, v198
	v_fmac_f32_e32 v187, v25, v199
	global_store_dwordx4 v0, v[184:187], s[38:39] nt
	s_add_u32 s38, s38, 0x4000
	s_addc_u32 s39, s39, 0
	v_fmac_f32_e32 v188, v26, v196
	v_fmac_f32_e32 v189, v27, v197
	v_fmac_f32_e32 v190, v28, v198
	v_fmac_f32_e32 v191, v29, v199
	global_store_dwordx4 v0, v[188:191], s[38:39] nt
	s_add_u32 s38, s38, 0x4000
	s_addc_u32 s39, s39, 0
	v_fmac_f32_e32 v192, v30, v196
	v_fmac_f32_e32 v193, v31, v197
	v_fmac_f32_e32 v194, v32, v198
	v_fmac_f32_e32 v195, v33, v199
	global_store_dwordx4 v0, v[192:195], s[38:39] nt
	s_add_u32 s38, s38, 0x4000
	s_addc_u32 s39, s39, 0
	s_add_i32 s34, s34, s30
	s_cmp_ge_i32 s34, s35
	s_cbranch_scc0 .LBB0_52
